# v55: v54 + phase-1 inner trip drops the now-redundant s_waitcnt vmcnt(0) before the bias add (s_nop 0 re-pad after the loop)
# baseline (speedup 1.0000x reference)
; __device__ __forceinline__ float dot4(const f32x4 a, const f32x4 b) { return (a[0] * b[0] + a[1] * b[1]) + (a[2] * b[2] + a[3] * b[3]); }
; __device__ __forceinline__ void norm_rows2(const f32x4 (&xa)[4], const f32x4 (&xb)[4], const LAS float* gsa, const LAS float* sha, const LAS float* gsb, const LAS float* shb, const LAS float* WgT, ...
;     float ssa = 0.f, ssb = 0.f;
; #pragma unroll
;     for (int i = 0; i < 4; ++i) { ssa += dot4(xa[i], xa[i]); ssb += dot4(xb[i], xb[i]); }
;     ssa = wave_sum(ssa); ssb = wave_sum(ssb);
;     const float ra = rsqrtf(ssa * (1.0f / 1024.0f) + 1e-6f), rb = rsqrtf(ssb * (1.0f / 1024.0f) + 1e-6f);
; __device__ void phase1(const Params& p, LAS unsigned char* lds) {
;     ...
;             const int ra_ = pr < 4 ? rbase + 2 * pr : rbase + 7;
;             const float* xa_ = p.x + (size_t)ra_ * 1024; const float* xb_ = pr < 4 ? xa_ + 1024 : p.ctx + (size_t)crow * 1024;
;             f32x4 xa[4], xb[4];
; #pragma unroll
;             for (int i = 0; i < 4; ++i) { xa[i] = __builtin_nontemporal_load((const f32x4*)(xa_ + i * 256 + lane * 4)); xb[i] = __builtin_nontemporal_load((const f32x4*)(xb_ + i * 256 + lane * 4)); }
.LBB0_110:
	s_add_i32 s28, 0, 0x2000
	s_add_i32 s29, 0, 0x3000
	s_add_i32 s30, 0, 0x1000
	s_cmp_eq_u32 s82, 8
	v_add_u32_e32 v0, s82, v105
	s_cselect_b64 vcc, -1, 0
	v_cndmask_b32_e32 v60, v0, v108, vcc
	v_ashrrev_i32_e32 v61, 31, v60
	v_lshlrev_b64 v[0:1], 12, v[60:61]
	v_lshl_add_u64 v[0:1], s[36:37], 0, v[0:1]
	v_mov_b32_e32 v49, v35
	s_waitcnt lgkmcnt(0)
	v_lshl_add_u64 v[2:3], v[0:1], 0, v[48:49]
	s_mov_b64 s[38:39], 0x1000
	global_load_dwordx4 v[24:27], v[2:3], off nt
	global_load_dwordx4 v[20:23], v[2:3], off offset:1024 nt
	global_load_dwordx4 v[4:7], v[2:3], off offset:3072 nt
	global_load_dwordx4 v[12:15], v[2:3], off offset:2048 nt
	v_lshl_add_u64 v[0:1], v[0:1], 0, s[38:39]
	v_cndmask_b32_e32 v1, v1, v59, vcc
	v_cndmask_b32_e32 v0, v0, v58, vcc
	v_lshl_add_u64 v[8:9], v[0:1], 0, v[48:49]
	global_load_dwordx4 v[28:31], v[8:9], off nt
	global_load_dwordx4 v[16:19], v[8:9], off offset:1024 nt
	global_load_dwordx4 v[0:3], v[8:9], off offset:3072 nt
	s_nop 0
	global_load_dwordx4 v[8:11], v[8:9], off offset:2048 nt
	s_and_b64 s[38:39], vcc, exec
	s_cselect_b32 s28, s28, 0
	s_cselect_b32 s29, s29, s30
	s_waitcnt vmcnt(7)
	v_pk_mul_f32 v[62:63], v[26:27], v[26:27]
	v_pk_mul_f32 v[64:65], v[24:25], v[24:25]
	s_waitcnt vmcnt(6)
	v_pk_mul_f32 v[66:67], v[22:23], v[22:23]
	v_pk_mul_f32 v[68:69], v[20:21], v[20:21]
	s_waitcnt vmcnt(4)
	v_mul_f32_e32 v70, v15, v15
	v_pk_mov_b32 v[72:73], v[64:65], v[62:63] op_sel:[1,0]
	v_mov_b32_e32 v65, v63
	v_pk_mov_b32 v[62:63], v[68:69], v[66:67] op_sel:[1,0]
	v_mov_b32_e32 v69, v67
	v_mul_f32_e32 v80, v7, v7
	v_mul_f32_e32 v34, v13, v13
	v_pk_fma_f32 v[70:71], v[14:15], v[14:15], v[70:71] op_sel_hi:[1,1,0]
	v_pk_add_f32 v[64:65], v[72:73], v[64:65]
	s_waitcnt vmcnt(3)
	v_pk_mul_f32 v[72:73], v[30:31], v[30:31]
	v_pk_mul_f32 v[74:75], v[28:29], v[28:29]
	v_pk_add_f32 v[62:63], v[62:63], v[68:69]
	s_waitcnt vmcnt(2)
	v_pk_mul_f32 v[68:69], v[18:19], v[18:19]
	v_pk_mul_f32 v[76:77], v[16:17], v[16:17]
	v_mul_f32_e32 v49, v4, v4
	v_mul_f32_e32 v79, v5, v5
	v_mul_f32_e32 v78, v6, v6
	v_pk_fma_f32 v[66:67], v[12:13], v[12:13], v[34:35] op_sel_hi:[1,1,0]
	v_mov_b32_e32 v71, v80
	v_pk_mov_b32 v[80:81], v[74:75], v[72:73] op_sel:[1,0]
	v_mov_b32_e32 v75, v73
	v_pk_mov_b32 v[72:73], v[76:77], v[68:69] op_sel:[1,0]
	v_mov_b32_e32 v77, v69
	v_pk_add_f32 v[64:65], v[64:65], v[64:65] op_sel:[0,1] op_sel_hi:[1,0]
	v_pk_add_f32 v[62:63], v[62:63], v[62:63] op_sel:[0,1] op_sel_hi:[1,0]
	v_mov_b32_e32 v67, v78
	s_waitcnt vmcnt(0)
	v_mul_f32_e32 v34, v9, v9
	v_mul_f32_e32 v78, v11, v11
	v_pk_add_f32 v[74:75], v[80:81], v[74:75]
	v_pk_add_f32 v[72:73], v[72:73], v[76:77]
	v_mov_b32_e32 v65, v49
	v_mov_b32_e32 v63, v79
	v_mul_f32_e32 v82, v0, v0
	v_mul_f32_e32 v83, v1, v1
	v_mul_f32_e32 v84, v2, v2
	v_mul_f32_e32 v85, v3, v3
	v_pk_add_f32 v[66:67], v[66:67], v[70:71]
	v_pk_fma_f32 v[68:69], v[8:9], v[8:9], v[34:35] op_sel_hi:[1,1,0]
	v_pk_fma_f32 v[70:71], v[10:11], v[10:11], v[78:79] op_sel_hi:[1,1,0]
	v_pk_add_f32 v[62:63], v[64:65], v[62:63]
	v_pk_add_f32 v[64:65], v[74:75], v[74:75] op_sel:[0,1] op_sel_hi:[1,0]
	v_pk_add_f32 v[72:73], v[72:73], v[72:73] op_sel:[0,1] op_sel_hi:[1,0]
	v_mov_b32_e32 v69, v84
	v_mov_b32_e32 v71, v85
	v_mov_b32_e32 v65, v82
	v_mov_b32_e32 v73, v83
	v_pk_add_f32 v[68:69], v[68:69], v[70:71]
	v_pk_add_f32 v[64:65], v[64:65], v[72:73]
	v_pk_add_f32 v[62:63], v[62:63], v[66:67]
	v_pk_add_f32 v[64:65], v[64:65], v[68:69]
	v_mov_b32_e32 v67, v62
	v_mov_b32_e32 v66, v64
	v_mov_b32_e32 v62, v65
	v_pk_add_f32 v[62:63], v[66:67], v[62:63]
	v_lshlrev_b64 v[76:77], 11, v[60:61]
	v_add_u32_e32 v49, s28, v48
	v_add_u32_e32 v61, s29, v48
	v_add_u32_e32 v34, 1, v60
	ds_read_b128 v[64:67], v99
	ds_read_b128 v[68:71], v99 offset:4096
	ds_read_b128 v[80:83], v49
	ds_read_b128 v[84:87], v61
	v_add_f32_dpp v62, v62, v62 row_mirror row_mask:0xf bank_mask:0xf
	v_add_f32_dpp v63, v63, v63 row_mirror row_mask:0xf bank_mask:0xf
	v_cndmask_b32_e32 v74, v34, v109, vcc
	v_add_f32_dpp v62, v62, v62 row_half_mirror row_mask:0xf bank_mask:0xf
	v_add_f32_dpp v63, v63, v63 row_half_mirror row_mask:0xf bank_mask:0xf
	v_ashrrev_i32_e32 v75, 31, v74
	v_add_f32_dpp v62, v62, v62 quad_perm:[1,0,3,2] row_mask:0xf bank_mask:0xf
	v_add_f32_dpp v63, v63, v63 quad_perm:[1,0,3,2] row_mask:0xf bank_mask:0xf
	v_lshlrev_b64 v[74:75], 11, v[74:75]
	v_add_f32_dpp v62, v62, v62 quad_perm:[2,3,0,1] row_mask:0xf bank_mask:0xf
	v_add_f32_dpp v63, v63, v63 quad_perm:[2,3,0,1] row_mask:0xf bank_mask:0xf
	v_lshl_add_u64 v[78:79], v[36:37], 0, v[76:77]
	s_nop 0
	v_readlane_b32 s54, v62, 0
	v_readlane_b32 s55, v62, 16
	v_readlane_b32 s56, v62, 32
	v_readlane_b32 s57, v62, 48
	v_readlane_b32 s58, v63, 0
	v_readlane_b32 s59, v63, 16
	v_readlane_b32 s60, v63, 32
	v_readlane_b32 s61, v63, 48
	v_mov_b32_e32 v62, s54
	v_mov_b32_e32 v63, s58
	v_add_f32_e32 v62, s55, v62
	v_add_f32_e32 v63, s59, v63
	v_add_f32_e32 v62, s56, v62
	v_add_f32_e32 v63, s60, v63
	v_add_f32_e32 v62, s57, v62
	v_add_f32_e32 v63, s61, v63
	s_waitcnt lgkmcnt(0)
; #define LAS __attribute__((address_space(3)))
; __device__ __forceinline__ unsigned cvt_pk_bf16(float lo, float hi) { unsigned r; asm volatile("v_cvt_pk_bf16_f32 %0, %1, %2" : "=v"(r) : "v"(lo), "v"(hi)); return r; }
; __device__ __forceinline__ float dot4(const f32x4 a, const f32x4 b) { return (a[0] * b[0] + a[1] * b[1]) + (a[2] * b[2] + a[3] * b[3]); }
; __device__ __forceinline__ void norm_rows2(const f32x4 (&xa)[4], const f32x4 (&xb)[4], const LAS float* gsa, const LAS float* sha, const LAS float* gsb, const LAS float* shb, const LAS float* WgT, ...
;     ...
;     const float ra = rsqrtf(ssa * (1.0f / 1024.0f) + 1e-6f), rb = rsqrtf(ssb * (1.0f / 1024.0f) + 1e-6f);
;     f32x4 ya[4], yb[4];
; #pragma unroll
;     for (int i = 0; i < 4; ++i) {
;         ya[i] = xa[i] * ra * *(const LAS f32x4*)(gsa + i * 256 + lane * 4) + *(const LAS f32x4*)(sha + i * 256 + lane * 4);
;         yb[i] = xb[i] * rb * *(const LAS f32x4*)(gsb + i * 256 + lane * 4) + *(const LAS f32x4*)(shb + i * 256 + lane * 4);
;         u32x2 w; w.x = cvt_pk_bf16(ya[i][0], ya[i][1]); w.y = cvt_pk_bf16(ya[i][2], ya[i][3]); *(u32x2*)(oa + i * 256 + lane * 4) = w;
;         u32x2 v; v.x = cvt_pk_bf16(yb[i][0], yb[i][1]); v.y = cvt_pk_bf16(yb[i][2], yb[i][3]); *(u32x2*)(ob + i * 256 + lane * 4) = v; }
;     f32x4 pa[4], pb[4];
; #pragma unroll
;     for (int jq = 0; jq < 4; ++jq) { f32x4 sa = (f32x4){0.f, 0.f, 0.f, 0.f}, sb = sa;
; #pragma unroll
;         for (int i = 0; i < 4; ++i) { const LAS float* wp = WgT + (jq * 4) * 1024 + i * 256 + lane * 4;
;             const f32x4 w0 = *(const LAS f32x4*)wp, w1 = *(const LAS f32x4*)(wp + 1024), w2 = *(const LAS f32x4*)(wp + 2048), w3 = *(const LAS f32x4*)(wp + 3072);
;             sa += (f32x4){dot4(ya[i], w0), dot4(ya[i], w1), dot4(ya[i], w2), dot4(ya[i], w3)};
;             sb += (f32x4){dot4(yb[i], w0), dot4(yb[i], w1), dot4(yb[i], w2), dot4(yb[i], w3)}; }
	s_nop 0
	v_pk_fma_f32 v[62:63], v[62:63], s[46:47], v[50:51] op_sel_hi:[1,0,0]
	s_nop 0
	v_mul_f32_e32 v72, 0x4b800000, v63
	v_cmp_gt_f32_e64 s[28:29], s34, v63
	v_mul_f32_e32 v73, 0x4b800000, v62
	v_cmp_gt_f32_e64 s[30:31], s34, v62
	v_cndmask_b32_e64 v63, v63, v72, s[28:29]
	v_rsq_f32_e32 v72, v63
	v_cndmask_b32_e64 v62, v62, v73, s[30:31]
	v_rsq_f32_e32 v73, v62
	v_lshl_add_u64 v[62:63], v[36:37], 0, v[74:75]
	v_mul_f32_e32 v74, 0x45800000, v72
	v_cndmask_b32_e64 v88, v72, v74, s[28:29]
	v_mul_f32_e32 v75, 0x45800000, v73
	v_cndmask_b32_e64 v90, v73, v75, s[30:31]
	v_pk_mul_f32 v[24:25], v[24:25], v[88:89] op_sel_hi:[1,0]
	v_pk_mul_f32 v[26:27], v[26:27], v[88:89] op_sel_hi:[1,0]
	v_pk_mul_f32 v[28:29], v[28:29], v[90:91] op_sel_hi:[1,0]
	v_pk_mul_f32 v[30:31], v[30:31], v[90:91] op_sel_hi:[1,0]
	v_pk_mul_f32 v[92:93], v[20:21], v[88:89] op_sel_hi:[1,0]
	v_pk_fma_f32 v[74:75], v[66:67], v[26:27], v[70:71]
	v_pk_fma_f32 v[76:77], v[64:65], v[24:25], v[68:69]
	v_pk_mul_f32 v[110:111], v[22:23], v[88:89] op_sel_hi:[1,0]
	v_cvt_pk_bf16_f32 v20, v76, v77
	v_cvt_pk_bf16_f32 v21, v74, v75
	v_pk_fma_f32 v[70:71], v[82:83], v[30:31], v[86:87]
	v_pk_fma_f32 v[72:73], v[80:81], v[28:29], v[84:85]
	global_store_dwordx2 v[78:79], v[20:21], off
	v_cvt_pk_bf16_f32 v64, v72, v73
	v_cvt_pk_bf16_f32 v65, v70, v71
	ds_read_b128 v[20:23], v99 offset:1024
	ds_read_b128 v[24:27], v99 offset:5120
	ds_read_b128 v[28:31], v49 offset:1024
	ds_read_b128 v[80:83], v61 offset:1024
	v_pk_mul_f32 v[16:17], v[16:17], v[90:91] op_sel_hi:[1,0]
	global_store_dwordx2 v[62:63], v[64:65], off
	v_pk_mul_f32 v[18:19], v[18:19], v[90:91] op_sel_hi:[1,0]
	s_waitcnt lgkmcnt(2)
	v_pk_fma_f32 v[66:67], v[110:111], v[22:23], v[26:27]
	v_pk_fma_f32 v[68:69], v[92:93], v[20:21], v[24:25]
	s_waitcnt lgkmcnt(0)
	v_pk_fma_f32 v[64:65], v[16:17], v[28:29], v[80:81]
	v_cvt_pk_bf16_f32 v16, v68, v69
	v_cvt_pk_bf16_f32 v17, v66, v67
	v_pk_fma_f32 v[30:31], v[18:19], v[30:31], v[82:83]
	global_store_dwordx2 v[78:79], v[16:17], off offset:512
	v_cvt_pk_bf16_f32 v16, v64, v65
	v_cvt_pk_bf16_f32 v17, v30, v31
	global_store_dwordx2 v[62:63], v[16:17], off offset:512
	ds_read_b128 v[16:19], v99 offset:2048
	ds_read_b128 v[20:23], v99 offset:6144
	ds_read_b128 v[24:27], v49 offset:2048
	ds_read_b128 v[80:83], v61 offset:2048
	v_pk_mul_f32 v[12:13], v[12:13], v[88:89] op_sel_hi:[1,0]
	v_pk_mul_f32 v[14:15], v[14:15], v[88:89] op_sel_hi:[1,0]
	v_pk_mul_f32 v[8:9], v[8:9], v[90:91] op_sel_hi:[1,0]
	s_waitcnt lgkmcnt(2)
	v_pk_fma_f32 v[14:15], v[14:15], v[18:19], v[22:23]
	v_pk_fma_f32 v[18:19], v[12:13], v[16:17], v[20:21]
	v_pk_mul_f32 v[10:11], v[10:11], v[90:91] op_sel_hi:[1,0]
	s_waitcnt lgkmcnt(0)
	v_pk_fma_f32 v[20:21], v[8:9], v[24:25], v[80:81]
	v_cvt_pk_bf16_f32 v8, v18, v19
	v_cvt_pk_bf16_f32 v9, v14, v15
	v_pk_fma_f32 v[16:17], v[10:11], v[26:27], v[82:83]
	global_store_dwordx2 v[78:79], v[8:9], off offset:1024
	v_cvt_pk_bf16_f32 v8, v20, v21
	v_cvt_pk_bf16_f32 v9, v16, v17
	global_store_dwordx2 v[62:63], v[8:9], off offset:1024
	ds_read_b128 v[8:11], v99 offset:3072
	ds_read_b128 v[22:25], v99 offset:7168
	v_pk_mul_f32 v[12:13], v[4:5], v[88:89] op_sel_hi:[1,0]
	v_pk_mul_f32 v[80:81], v[6:7], v[88:89] op_sel_hi:[1,0]
	ds_read_b128 v[4:7], v49 offset:3072
	ds_read_b128 v[26:29], v61 offset:3072
	v_pk_mul_f32 v[0:1], v[0:1], v[90:91] op_sel_hi:[1,0]
	s_waitcnt lgkmcnt(2)
	v_pk_fma_f32 v[10:11], v[80:81], v[10:11], v[24:25]
	v_pk_fma_f32 v[12:13], v[12:13], v[8:9], v[22:23]
	v_pk_mul_f32 v[2:3], v[2:3], v[90:91] op_sel_hi:[1,0]
	s_waitcnt lgkmcnt(0)
	v_pk_fma_f32 v[8:9], v[0:1], v[4:5], v[26:27]
	v_cvt_pk_bf16_f32 v0, v12, v13
	v_cvt_pk_bf16_f32 v1, v10, v11
	v_pk_fma_f32 v[6:7], v[2:3], v[6:7], v[28:29]
	global_store_dwordx2 v[78:79], v[0:1], off offset:1536
	v_cvt_pk_bf16_f32 v4, v8, v9
	v_cvt_pk_bf16_f32 v5, v6, v7
	global_store_dwordx2 v[62:63], v[4:5], off offset:1536
	ds_read_b128 v[110:113], v99 offset:16384
	ds_read_b128 v[114:117], v99 offset:20480
	ds_read_b128 v[118:121], v99 offset:24576
	ds_read_b128 v[122:125], v99 offset:28672
	ds_read_b128 v[126:129], v99 offset:32768
	ds_read_b128 v[130:133], v99 offset:36864
	ds_read_b128 v[134:137], v99 offset:40960
	ds_read_b128 v[138:141], v99 offset:45056
	ds_read_b128 v[142:145], v99 offset:49152
	ds_read_b128 v[146:149], v99 offset:53248
	ds_read_b128 v[150:153], v99 offset:57344
	ds_read_b128 v[154:157], v99 offset:61440
	s_waitcnt lgkmcnt(8)
	v_pk_mul_f32 v[160:161], v[72:73], v[110:111]
	v_pk_mul_f32 v[192:193], v[76:77], v[110:111]
	v_pk_mul_f32 v[162:163], v[72:73], v[114:115]
	v_pk_mul_f32 v[194:195], v[76:77], v[114:115]
	v_pk_mul_f32 v[164:165], v[72:73], v[118:119]
	v_pk_mul_f32 v[196:197], v[76:77], v[118:119]
	v_pk_mul_f32 v[166:167], v[72:73], v[122:123]
	v_pk_mul_f32 v[198:199], v[76:77], v[122:123]
	v_pk_fma_f32 v[160:161], v[70:71], v[112:113], v[160:161]
	v_pk_fma_f32 v[192:193], v[74:75], v[112:113], v[192:193]
	v_pk_fma_f32 v[162:163], v[70:71], v[116:117], v[162:163]
	v_pk_fma_f32 v[194:195], v[74:75], v[116:117], v[194:195]
	v_pk_fma_f32 v[164:165], v[70:71], v[120:121], v[164:165]
	v_pk_fma_f32 v[196:197], v[74:75], v[120:121], v[196:197]
	v_pk_fma_f32 v[166:167], v[70:71], v[124:125], v[166:167]
	v_pk_fma_f32 v[198:199], v[74:75], v[124:125], v[198:199]
	ds_read_b128 v[228:231], v100 offset:49152
	ds_read_b128 v[232:235], v100 offset:53248
	ds_read_b128 v[236:239], v100 offset:57344
	ds_read_b128 v[240:243], v100 offset:61440
	s_waitcnt lgkmcnt(8)
; #define LAS __attribute__((address_space(3)))
; __device__ __forceinline__ float dot4(const f32x4 a, const f32x4 b) { return (a[0] * b[0] + a[1] * b[1]) + (a[2] * b[2] + a[3] * b[3]); }
; __device__ __forceinline__ void norm_rows2(const f32x4 (&xa)[4], const f32x4 (&xb)[4], const LAS float* gsa, const LAS float* sha, const LAS float* gsb, const LAS float* shb, const LAS float* WgT, ...
;     ...
;     for (int jq = 0; jq < 4; ++jq) { f32x4 sa = (f32x4){0.f, 0.f, 0.f, 0.f}, sb = sa;
; #pragma unroll
;         for (int i = 0; i < 4; ++i) { const LAS float* wp = WgT + (jq * 4) * 1024 + i * 256 + lane * 4;
;             const f32x4 w0 = *(const LAS f32x4*)wp, w1 = *(const LAS f32x4*)(wp + 1024), w2 = *(const LAS f32x4*)(wp + 2048), w3 = *(const LAS f32x4*)(wp + 3072);
;             sa += (f32x4){dot4(ya[i], w0), dot4(ya[i], w1), dot4(ya[i], w2), dot4(ya[i], w3)};
;             sb += (f32x4){dot4(yb[i], w0), dot4(yb[i], w1), dot4(yb[i], w2), dot4(yb[i], w3)}; }
;         pa[jq] = sa; pb[jq] = sb; }
	v_pk_mul_f32 v[168:169], v[72:73], v[126:127]
	v_pk_mul_f32 v[200:201], v[76:77], v[126:127]
	v_pk_mul_f32 v[170:171], v[72:73], v[130:131]
	v_pk_mul_f32 v[202:203], v[76:77], v[130:131]
	v_pk_mul_f32 v[172:173], v[72:73], v[134:135]
	v_pk_mul_f32 v[204:205], v[76:77], v[134:135]
	v_pk_mul_f32 v[174:175], v[72:73], v[138:139]
	v_pk_mul_f32 v[206:207], v[76:77], v[138:139]
	v_pk_fma_f32 v[168:169], v[70:71], v[128:129], v[168:169]
	v_pk_fma_f32 v[200:201], v[74:75], v[128:129], v[200:201]
	v_pk_fma_f32 v[170:171], v[70:71], v[132:133], v[170:171]
	v_pk_fma_f32 v[202:203], v[74:75], v[132:133], v[202:203]
	v_pk_fma_f32 v[172:173], v[70:71], v[136:137], v[172:173]
	v_pk_fma_f32 v[204:205], v[74:75], v[136:137], v[204:205]
	v_pk_fma_f32 v[174:175], v[70:71], v[140:141], v[174:175]
	v_pk_fma_f32 v[206:207], v[74:75], v[140:141], v[206:207]
	ds_read_b128 v[110:113], v99 offset:17408
	ds_read_b128 v[114:117], v99 offset:21504
	ds_read_b128 v[118:121], v99 offset:25600
	ds_read_b128 v[122:125], v99 offset:29696
	s_waitcnt lgkmcnt(8)
	v_pk_mul_f32 v[176:177], v[72:73], v[142:143]
	v_pk_mul_f32 v[208:209], v[76:77], v[142:143]
	v_pk_mul_f32 v[178:179], v[72:73], v[146:147]
	v_pk_mul_f32 v[210:211], v[76:77], v[146:147]
	v_pk_mul_f32 v[180:181], v[72:73], v[150:151]
	v_pk_mul_f32 v[212:213], v[76:77], v[150:151]
	v_pk_mul_f32 v[182:183], v[72:73], v[154:155]
	v_pk_mul_f32 v[214:215], v[76:77], v[154:155]
	v_pk_fma_f32 v[176:177], v[70:71], v[144:145], v[176:177]
	v_pk_fma_f32 v[208:209], v[74:75], v[144:145], v[208:209]
	v_pk_fma_f32 v[178:179], v[70:71], v[148:149], v[178:179]
	v_pk_fma_f32 v[210:211], v[74:75], v[148:149], v[210:211]
	v_pk_fma_f32 v[180:181], v[70:71], v[152:153], v[180:181]
	v_pk_fma_f32 v[212:213], v[74:75], v[152:153], v[212:213]
	v_pk_fma_f32 v[182:183], v[70:71], v[156:157], v[182:183]
	v_pk_fma_f32 v[214:215], v[74:75], v[156:157], v[214:215]
	ds_read_b128 v[126:129], v99 offset:33792
	ds_read_b128 v[130:133], v99 offset:37888
	ds_read_b128 v[134:137], v99 offset:41984
	ds_read_b128 v[138:141], v99 offset:46080
	s_waitcnt lgkmcnt(8)
	v_pk_mul_f32 v[184:185], v[72:73], v[228:229]
	v_pk_mul_f32 v[216:217], v[76:77], v[228:229]
	v_pk_mul_f32 v[186:187], v[72:73], v[232:233]
	v_pk_mul_f32 v[218:219], v[76:77], v[232:233]
	v_pk_mul_f32 v[188:189], v[72:73], v[236:237]
	v_pk_mul_f32 v[220:221], v[76:77], v[236:237]
	v_pk_mul_f32 v[190:191], v[72:73], v[240:241]
	v_pk_mul_f32 v[222:223], v[76:77], v[240:241]
	v_pk_fma_f32 v[184:185], v[70:71], v[230:231], v[184:185]
	v_pk_fma_f32 v[216:217], v[74:75], v[230:231], v[216:217]
	v_pk_fma_f32 v[186:187], v[70:71], v[234:235], v[186:187]
	v_pk_fma_f32 v[218:219], v[74:75], v[234:235], v[218:219]
	v_pk_fma_f32 v[188:189], v[70:71], v[238:239], v[188:189]
	v_pk_fma_f32 v[220:221], v[74:75], v[238:239], v[220:221]
	v_pk_fma_f32 v[190:191], v[70:71], v[242:243], v[190:191]
	v_pk_fma_f32 v[222:223], v[74:75], v[242:243], v[222:223]
	ds_read_b128 v[142:145], v99 offset:50176
	ds_read_b128 v[146:149], v99 offset:54272
	ds_read_b128 v[150:153], v99 offset:58368
	ds_read_b128 v[154:157], v99 offset:62464
	s_waitcnt lgkmcnt(8)
	v_pk_fma_f32 v[160:161], v[64:65], v[110:111], v[160:161]
	v_pk_fma_f32 v[192:193], v[68:69], v[110:111], v[192:193]
	v_pk_fma_f32 v[162:163], v[64:65], v[114:115], v[162:163]
	v_pk_fma_f32 v[194:195], v[68:69], v[114:115], v[194:195]
	v_pk_fma_f32 v[164:165], v[64:65], v[118:119], v[164:165]
	v_pk_fma_f32 v[196:197], v[68:69], v[118:119], v[196:197]
	v_pk_fma_f32 v[166:167], v[64:65], v[122:123], v[166:167]
	v_pk_fma_f32 v[198:199], v[68:69], v[122:123], v[198:199]
	v_pk_fma_f32 v[160:161], v[30:31], v[112:113], v[160:161]
	v_pk_fma_f32 v[192:193], v[66:67], v[112:113], v[192:193]
	v_pk_fma_f32 v[162:163], v[30:31], v[116:117], v[162:163]
	v_pk_fma_f32 v[194:195], v[66:67], v[116:117], v[194:195]
	v_pk_fma_f32 v[164:165], v[30:31], v[120:121], v[164:165]
	v_pk_fma_f32 v[196:197], v[66:67], v[120:121], v[196:197]
	v_pk_fma_f32 v[166:167], v[30:31], v[124:125], v[166:167]
	v_pk_fma_f32 v[198:199], v[66:67], v[124:125], v[198:199]
	ds_read_b128 v[228:231], v100 offset:50176
	ds_read_b128 v[232:235], v100 offset:54272
	ds_read_b128 v[236:239], v100 offset:58368
	ds_read_b128 v[240:243], v100 offset:62464
	s_waitcnt lgkmcnt(8)
	v_pk_fma_f32 v[168:169], v[64:65], v[126:127], v[168:169]
	v_pk_fma_f32 v[200:201], v[68:69], v[126:127], v[200:201]
	v_pk_fma_f32 v[170:171], v[64:65], v[130:131], v[170:171]
	v_pk_fma_f32 v[202:203], v[68:69], v[130:131], v[202:203]
	v_pk_fma_f32 v[172:173], v[64:65], v[134:135], v[172:173]
	v_pk_fma_f32 v[204:205], v[68:69], v[134:135], v[204:205]
	v_pk_fma_f32 v[174:175], v[64:65], v[138:139], v[174:175]
	v_pk_fma_f32 v[206:207], v[68:69], v[138:139], v[206:207]
	v_pk_fma_f32 v[168:169], v[30:31], v[128:129], v[168:169]
	v_pk_fma_f32 v[200:201], v[66:67], v[128:129], v[200:201]
	v_pk_fma_f32 v[170:171], v[30:31], v[132:133], v[170:171]
	v_pk_fma_f32 v[202:203], v[66:67], v[132:133], v[202:203]
	v_pk_fma_f32 v[172:173], v[30:31], v[136:137], v[172:173]
	v_pk_fma_f32 v[204:205], v[66:67], v[136:137], v[204:205]
	v_pk_fma_f32 v[174:175], v[30:31], v[140:141], v[174:175]
	v_pk_fma_f32 v[206:207], v[66:67], v[140:141], v[206:207]
	ds_read_b128 v[110:113], v99 offset:18432
	ds_read_b128 v[114:117], v99 offset:22528
	ds_read_b128 v[118:121], v99 offset:26624
	ds_read_b128 v[122:125], v99 offset:30720
	s_waitcnt lgkmcnt(8)
; #define LAS __attribute__((address_space(3)))
; __device__ __forceinline__ float dot4(const f32x4 a, const f32x4 b) { return (a[0] * b[0] + a[1] * b[1]) + (a[2] * b[2] + a[3] * b[3]); }
; __device__ __forceinline__ void norm_rows2(const f32x4 (&xa)[4], const f32x4 (&xb)[4], const LAS float* gsa, const LAS float* sha, const LAS float* gsb, const LAS float* shb, const LAS float* WgT, ...
;     ...
;     for (int jq = 0; jq < 4; ++jq) { f32x4 sa = (f32x4){0.f, 0.f, 0.f, 0.f}, sb = sa;
; #pragma unroll
;         for (int i = 0; i < 4; ++i) { const LAS float* wp = WgT + (jq * 4) * 1024 + i * 256 + lane * 4;
;             const f32x4 w0 = *(const LAS f32x4*)wp, w1 = *(const LAS f32x4*)(wp + 1024), w2 = *(const LAS f32x4*)(wp + 2048), w3 = *(const LAS f32x4*)(wp + 3072);
;             sa += (f32x4){dot4(ya[i], w0), dot4(ya[i], w1), dot4(ya[i], w2), dot4(ya[i], w3)};
;             sb += (f32x4){dot4(yb[i], w0), dot4(yb[i], w1), dot4(yb[i], w2), dot4(yb[i], w3)}; }
;         pa[jq] = sa; pb[jq] = sb; }
	v_pk_fma_f32 v[176:177], v[64:65], v[142:143], v[176:177]
	v_pk_fma_f32 v[208:209], v[68:69], v[142:143], v[208:209]
	v_pk_fma_f32 v[178:179], v[64:65], v[146:147], v[178:179]
	v_pk_fma_f32 v[210:211], v[68:69], v[146:147], v[210:211]
	v_pk_fma_f32 v[180:181], v[64:65], v[150:151], v[180:181]
	v_pk_fma_f32 v[212:213], v[68:69], v[150:151], v[212:213]
	v_pk_fma_f32 v[182:183], v[64:65], v[154:155], v[182:183]
	v_pk_fma_f32 v[214:215], v[68:69], v[154:155], v[214:215]
	v_pk_fma_f32 v[176:177], v[30:31], v[144:145], v[176:177]
	v_pk_fma_f32 v[208:209], v[66:67], v[144:145], v[208:209]
	v_pk_fma_f32 v[178:179], v[30:31], v[148:149], v[178:179]
	v_pk_fma_f32 v[210:211], v[66:67], v[148:149], v[210:211]
	v_pk_fma_f32 v[180:181], v[30:31], v[152:153], v[180:181]
	v_pk_fma_f32 v[212:213], v[66:67], v[152:153], v[212:213]
	v_pk_fma_f32 v[182:183], v[30:31], v[156:157], v[182:183]
	v_pk_fma_f32 v[214:215], v[66:67], v[156:157], v[214:215]
	ds_read_b128 v[126:129], v99 offset:34816
	ds_read_b128 v[130:133], v99 offset:38912
	ds_read_b128 v[134:137], v99 offset:43008
	ds_read_b128 v[138:141], v99 offset:47104
	s_waitcnt lgkmcnt(8)
	v_pk_fma_f32 v[184:185], v[64:65], v[228:229], v[184:185]
	v_pk_fma_f32 v[216:217], v[68:69], v[228:229], v[216:217]
	v_pk_fma_f32 v[186:187], v[64:65], v[232:233], v[186:187]
	v_pk_fma_f32 v[218:219], v[68:69], v[232:233], v[218:219]
	v_pk_fma_f32 v[188:189], v[64:65], v[236:237], v[188:189]
	v_pk_fma_f32 v[220:221], v[68:69], v[236:237], v[220:221]
	v_pk_fma_f32 v[190:191], v[64:65], v[240:241], v[190:191]
	v_pk_fma_f32 v[222:223], v[68:69], v[240:241], v[222:223]
	v_pk_fma_f32 v[184:185], v[30:31], v[230:231], v[184:185]
	v_pk_fma_f32 v[216:217], v[66:67], v[230:231], v[216:217]
	v_pk_fma_f32 v[186:187], v[30:31], v[234:235], v[186:187]
	v_pk_fma_f32 v[218:219], v[66:67], v[234:235], v[218:219]
	v_pk_fma_f32 v[188:189], v[30:31], v[238:239], v[188:189]
	v_pk_fma_f32 v[220:221], v[66:67], v[238:239], v[220:221]
	v_pk_fma_f32 v[190:191], v[30:31], v[242:243], v[190:191]
	v_pk_fma_f32 v[222:223], v[66:67], v[242:243], v[222:223]
	ds_read_b128 v[142:145], v99 offset:51200
	ds_read_b128 v[146:149], v99 offset:55296
	ds_read_b128 v[150:153], v99 offset:59392
	ds_read_b128 v[154:157], v99 offset:63488
	s_waitcnt lgkmcnt(8)
	v_pk_fma_f32 v[160:161], v[20:21], v[110:111], v[160:161]
	v_pk_fma_f32 v[192:193], v[18:19], v[110:111], v[192:193]
	v_pk_fma_f32 v[162:163], v[20:21], v[114:115], v[162:163]
	v_pk_fma_f32 v[194:195], v[18:19], v[114:115], v[194:195]
	v_pk_fma_f32 v[164:165], v[20:21], v[118:119], v[164:165]
	v_pk_fma_f32 v[196:197], v[18:19], v[118:119], v[196:197]
	v_pk_fma_f32 v[166:167], v[20:21], v[122:123], v[166:167]
	v_pk_fma_f32 v[198:199], v[18:19], v[122:123], v[198:199]
	v_pk_fma_f32 v[160:161], v[16:17], v[112:113], v[160:161]
	v_pk_fma_f32 v[192:193], v[14:15], v[112:113], v[192:193]
	v_pk_fma_f32 v[162:163], v[16:17], v[116:117], v[162:163]
	v_pk_fma_f32 v[194:195], v[14:15], v[116:117], v[194:195]
	v_pk_fma_f32 v[164:165], v[16:17], v[120:121], v[164:165]
	v_pk_fma_f32 v[196:197], v[14:15], v[120:121], v[196:197]
	v_pk_fma_f32 v[166:167], v[16:17], v[124:125], v[166:167]
	v_pk_fma_f32 v[198:199], v[14:15], v[124:125], v[198:199]
	ds_read_b128 v[228:231], v100 offset:51200
	ds_read_b128 v[232:235], v100 offset:55296
	ds_read_b128 v[236:239], v100 offset:59392
	ds_read_b128 v[240:243], v100 offset:63488
	s_waitcnt lgkmcnt(8)
	v_pk_fma_f32 v[168:169], v[20:21], v[126:127], v[168:169]
	v_pk_fma_f32 v[200:201], v[18:19], v[126:127], v[200:201]
	v_pk_fma_f32 v[170:171], v[20:21], v[130:131], v[170:171]
	v_pk_fma_f32 v[202:203], v[18:19], v[130:131], v[202:203]
	v_pk_fma_f32 v[172:173], v[20:21], v[134:135], v[172:173]
	v_pk_fma_f32 v[204:205], v[18:19], v[134:135], v[204:205]
	v_pk_fma_f32 v[174:175], v[20:21], v[138:139], v[174:175]
	v_pk_fma_f32 v[206:207], v[18:19], v[138:139], v[206:207]
	v_pk_fma_f32 v[168:169], v[16:17], v[128:129], v[168:169]
	v_pk_fma_f32 v[200:201], v[14:15], v[128:129], v[200:201]
	v_pk_fma_f32 v[170:171], v[16:17], v[132:133], v[170:171]
	v_pk_fma_f32 v[202:203], v[14:15], v[132:133], v[202:203]
	v_pk_fma_f32 v[172:173], v[16:17], v[136:137], v[172:173]
	v_pk_fma_f32 v[204:205], v[14:15], v[136:137], v[204:205]
	v_pk_fma_f32 v[174:175], v[16:17], v[140:141], v[174:175]
	v_pk_fma_f32 v[206:207], v[14:15], v[140:141], v[206:207]
	ds_read_b128 v[110:113], v99 offset:19456
	ds_read_b128 v[114:117], v99 offset:23552
	ds_read_b128 v[118:121], v99 offset:27648
	ds_read_b128 v[122:125], v99 offset:31744
	s_waitcnt lgkmcnt(8)
	v_pk_fma_f32 v[176:177], v[20:21], v[142:143], v[176:177]
	v_pk_fma_f32 v[208:209], v[18:19], v[142:143], v[208:209]
	v_pk_fma_f32 v[178:179], v[20:21], v[146:147], v[178:179]
	v_pk_fma_f32 v[210:211], v[18:19], v[146:147], v[210:211]
	v_pk_fma_f32 v[180:181], v[20:21], v[150:151], v[180:181]
	v_pk_fma_f32 v[212:213], v[18:19], v[150:151], v[212:213]
	v_pk_fma_f32 v[182:183], v[20:21], v[154:155], v[182:183]
	v_pk_fma_f32 v[214:215], v[18:19], v[154:155], v[214:215]
	v_pk_fma_f32 v[176:177], v[16:17], v[144:145], v[176:177]
	v_pk_fma_f32 v[208:209], v[14:15], v[144:145], v[208:209]
	v_pk_fma_f32 v[178:179], v[16:17], v[148:149], v[178:179]
	v_pk_fma_f32 v[210:211], v[14:15], v[148:149], v[210:211]
	v_pk_fma_f32 v[180:181], v[16:17], v[152:153], v[180:181]
	v_pk_fma_f32 v[212:213], v[14:15], v[152:153], v[212:213]
	v_pk_fma_f32 v[182:183], v[16:17], v[156:157], v[182:183]
	v_pk_fma_f32 v[214:215], v[14:15], v[156:157], v[214:215]
	ds_read_b128 v[126:129], v99 offset:35840
	ds_read_b128 v[130:133], v99 offset:39936
	ds_read_b128 v[134:137], v99 offset:44032
	ds_read_b128 v[138:141], v99 offset:48128
	s_waitcnt lgkmcnt(8)
; #define LAS __attribute__((address_space(3)))
; __device__ __forceinline__ float dot4(const f32x4 a, const f32x4 b) { return (a[0] * b[0] + a[1] * b[1]) + (a[2] * b[2] + a[3] * b[3]); }
; __device__ __forceinline__ void norm_rows2(const f32x4 (&xa)[4], const f32x4 (&xb)[4], const LAS float* gsa, const LAS float* sha, const LAS float* gsb, const LAS float* shb, const LAS float* WgT, ...
;     ...
;     for (int jq = 0; jq < 4; ++jq) { f32x4 sa = (f32x4){0.f, 0.f, 0.f, 0.f}, sb = sa;
; #pragma unroll
;         for (int i = 0; i < 4; ++i) { const LAS float* wp = WgT + (jq * 4) * 1024 + i * 256 + lane * 4;
;             const f32x4 w0 = *(const LAS f32x4*)wp, w1 = *(const LAS f32x4*)(wp + 1024), w2 = *(const LAS f32x4*)(wp + 2048), w3 = *(const LAS f32x4*)(wp + 3072);
;             sa += (f32x4){dot4(ya[i], w0), dot4(ya[i], w1), dot4(ya[i], w2), dot4(ya[i], w3)};
;             sb += (f32x4){dot4(yb[i], w0), dot4(yb[i], w1), dot4(yb[i], w2), dot4(yb[i], w3)}; }
;         pa[jq] = sa; pb[jq] = sb; }
	v_pk_fma_f32 v[184:185], v[20:21], v[228:229], v[184:185]
	v_pk_fma_f32 v[216:217], v[18:19], v[228:229], v[216:217]
	v_pk_fma_f32 v[186:187], v[20:21], v[232:233], v[186:187]
	v_pk_fma_f32 v[218:219], v[18:19], v[232:233], v[218:219]
	v_pk_fma_f32 v[188:189], v[20:21], v[236:237], v[188:189]
	v_pk_fma_f32 v[220:221], v[18:19], v[236:237], v[220:221]
	v_pk_fma_f32 v[190:191], v[20:21], v[240:241], v[190:191]
	v_pk_fma_f32 v[222:223], v[18:19], v[240:241], v[222:223]
	v_pk_fma_f32 v[184:185], v[16:17], v[230:231], v[184:185]
	v_pk_fma_f32 v[216:217], v[14:15], v[230:231], v[216:217]
	v_pk_fma_f32 v[186:187], v[16:17], v[234:235], v[186:187]
	v_pk_fma_f32 v[218:219], v[14:15], v[234:235], v[218:219]
	v_pk_fma_f32 v[188:189], v[16:17], v[238:239], v[188:189]
	v_pk_fma_f32 v[220:221], v[14:15], v[238:239], v[220:221]
	v_pk_fma_f32 v[190:191], v[16:17], v[242:243], v[190:191]
	v_pk_fma_f32 v[222:223], v[14:15], v[242:243], v[222:223]
	ds_read_b128 v[142:145], v99 offset:52224
	ds_read_b128 v[146:149], v99 offset:56320
	ds_read_b128 v[150:153], v99 offset:60416
	ds_read_b128 v[154:157], v99 offset:64512
	s_waitcnt lgkmcnt(8)
	v_pk_fma_f32 v[160:161], v[8:9], v[110:111], v[160:161]
	v_pk_fma_f32 v[192:193], v[12:13], v[110:111], v[192:193]
	v_pk_fma_f32 v[162:163], v[8:9], v[114:115], v[162:163]
	v_pk_fma_f32 v[194:195], v[12:13], v[114:115], v[194:195]
	v_pk_fma_f32 v[164:165], v[8:9], v[118:119], v[164:165]
	v_pk_fma_f32 v[196:197], v[12:13], v[118:119], v[196:197]
	v_pk_fma_f32 v[166:167], v[8:9], v[122:123], v[166:167]
	v_pk_fma_f32 v[198:199], v[12:13], v[122:123], v[198:199]
	v_pk_fma_f32 v[160:161], v[6:7], v[112:113], v[160:161]
	v_pk_fma_f32 v[192:193], v[10:11], v[112:113], v[192:193]
	v_pk_fma_f32 v[162:163], v[6:7], v[116:117], v[162:163]
	v_pk_fma_f32 v[194:195], v[10:11], v[116:117], v[194:195]
	v_pk_fma_f32 v[164:165], v[6:7], v[120:121], v[164:165]
	v_pk_fma_f32 v[196:197], v[10:11], v[120:121], v[196:197]
	v_pk_fma_f32 v[166:167], v[6:7], v[124:125], v[166:167]
	v_pk_fma_f32 v[198:199], v[10:11], v[124:125], v[198:199]
	ds_read_b128 v[228:231], v100 offset:52224
	ds_read_b128 v[232:235], v100 offset:56320
	ds_read_b128 v[236:239], v100 offset:60416
	ds_read_b128 v[240:243], v100 offset:64512
	s_waitcnt lgkmcnt(8)
	v_pk_fma_f32 v[168:169], v[8:9], v[126:127], v[168:169]
	v_pk_fma_f32 v[200:201], v[12:13], v[126:127], v[200:201]
	v_pk_fma_f32 v[170:171], v[8:9], v[130:131], v[170:171]
	v_pk_fma_f32 v[202:203], v[12:13], v[130:131], v[202:203]
	v_pk_fma_f32 v[172:173], v[8:9], v[134:135], v[172:173]
	v_pk_fma_f32 v[204:205], v[12:13], v[134:135], v[204:205]
	v_pk_fma_f32 v[174:175], v[8:9], v[138:139], v[174:175]
	v_pk_fma_f32 v[206:207], v[12:13], v[138:139], v[206:207]
	v_pk_fma_f32 v[168:169], v[6:7], v[128:129], v[168:169]
	v_pk_fma_f32 v[200:201], v[10:11], v[128:129], v[200:201]
	v_pk_fma_f32 v[170:171], v[6:7], v[132:133], v[170:171]
	v_pk_fma_f32 v[202:203], v[10:11], v[132:133], v[202:203]
	v_pk_fma_f32 v[172:173], v[6:7], v[136:137], v[172:173]
	v_pk_fma_f32 v[204:205], v[10:11], v[136:137], v[204:205]
	v_pk_fma_f32 v[174:175], v[6:7], v[140:141], v[174:175]
	v_pk_fma_f32 v[206:207], v[10:11], v[140:141], v[206:207]
	s_waitcnt lgkmcnt(4)
	v_pk_fma_f32 v[176:177], v[8:9], v[142:143], v[176:177]
	v_pk_fma_f32 v[208:209], v[12:13], v[142:143], v[208:209]
	v_pk_fma_f32 v[178:179], v[8:9], v[146:147], v[178:179]
	v_pk_fma_f32 v[210:211], v[12:13], v[146:147], v[210:211]
	v_pk_fma_f32 v[180:181], v[8:9], v[150:151], v[180:181]
	v_pk_fma_f32 v[212:213], v[12:13], v[150:151], v[212:213]
	v_pk_fma_f32 v[182:183], v[8:9], v[154:155], v[182:183]
	v_pk_fma_f32 v[214:215], v[12:13], v[154:155], v[214:215]
	v_pk_fma_f32 v[176:177], v[6:7], v[144:145], v[176:177]
	v_pk_fma_f32 v[208:209], v[10:11], v[144:145], v[208:209]
	v_pk_fma_f32 v[178:179], v[6:7], v[148:149], v[178:179]
	v_pk_fma_f32 v[210:211], v[10:11], v[148:149], v[210:211]
	v_pk_fma_f32 v[180:181], v[6:7], v[152:153], v[180:181]
	v_pk_fma_f32 v[212:213], v[10:11], v[152:153], v[212:213]
	v_pk_fma_f32 v[182:183], v[6:7], v[156:157], v[182:183]
	v_pk_fma_f32 v[214:215], v[10:11], v[156:157], v[214:215]
	s_waitcnt lgkmcnt(0)
	v_pk_fma_f32 v[184:185], v[8:9], v[228:229], v[184:185]
	v_pk_fma_f32 v[216:217], v[12:13], v[228:229], v[216:217]
	v_pk_fma_f32 v[186:187], v[8:9], v[232:233], v[186:187]
	v_pk_fma_f32 v[218:219], v[12:13], v[232:233], v[218:219]
	v_pk_fma_f32 v[188:189], v[8:9], v[236:237], v[188:189]
	v_pk_fma_f32 v[220:221], v[12:13], v[236:237], v[220:221]
	v_pk_fma_f32 v[190:191], v[8:9], v[240:241], v[190:191]
	v_pk_fma_f32 v[222:223], v[12:13], v[240:241], v[222:223]
	v_pk_fma_f32 v[184:185], v[6:7], v[230:231], v[184:185]
	v_pk_fma_f32 v[216:217], v[10:11], v[230:231], v[216:217]
	v_pk_fma_f32 v[186:187], v[6:7], v[234:235], v[186:187]
	v_pk_fma_f32 v[218:219], v[10:11], v[234:235], v[218:219]
	v_pk_fma_f32 v[188:189], v[6:7], v[238:239], v[188:189]
	v_pk_fma_f32 v[220:221], v[10:11], v[238:239], v[220:221]
	v_pk_fma_f32 v[190:191], v[6:7], v[242:243], v[190:191]
	v_pk_fma_f32 v[222:223], v[10:11], v[242:243], v[222:223]
	v_add_f32_e32 v22, v160, v161
	v_add_f32_e32 v23, v162, v163
	v_add_f32_e32 v24, v164, v165
	v_add_f32_e32 v25, v166, v167
	v_add_f32_e32 v78, v168, v169
	v_add_f32_e32 v79, v170, v171
	v_add_f32_e32 v80, v172, v173
	v_add_f32_e32 v81, v174, v175
	v_add_f32_e32 v86, v176, v177
	v_add_f32_e32 v87, v178, v179
	v_add_f32_e32 v88, v180, v181
	v_add_f32_e32 v89, v182, v183
	v_add_f32_e32 v2, v184, v185
	v_add_f32_e32 v3, v186, v187
	v_add_f32_e32 v0, v188, v189
	v_add_f32_e32 v1, v190, v191
	v_add_f32_e32 v26, v192, v193
	v_add_f32_e32 v27, v194, v195
; __device__ __forceinline__ float log_sigmoid(float x) { return fminf(x, 0.f) - log1pf(expf(-fabsf(x))); }
; __device__ __forceinline__ float bfly16(const f32x4 p0, const f32x4 p1, const f32x4 p2, const f32x4 p3, int lane) {
;     const bool b3 = lane & 8, b2 = lane & 4, b1 = lane & 2, b0 = lane & 1;
;     const f32x4 s0 = b3 ? p0 : p2, s1 = b3 ? p1 : p3, k0 = b3 ? p2 : p0, k1 = b3 ? p3 : p1;
;     f32x4 a, c;
;     a[0] = k0[0] + __shfl_xor(s0[0], 8); a[1] = k0[1] + __shfl_xor(s0[1], 8); a[2] = k0[2] + __shfl_xor(s0[2], 8); a[3] = k0[3] + __shfl_xor(s0[3], 8);
;     c[0] = k1[0] + __shfl_xor(s1[0], 8); c[1] = k1[1] + __shfl_xor(s1[1], 8); c[2] = k1[2] + __shfl_xor(s1[2], 8); c[3] = k1[3] + __shfl_xor(s1[3], 8);
;     const f32x4 s4 = b2 ? a : c, k4 = b2 ? c : a;
;     const float d0 = k4[0] + __shfl_xor(s4[0], 4), d1 = k4[1] + __shfl_xor(s4[1], 4), d2 = k4[2] + __shfl_xor(s4[2], 4), d3 = k4[3] + __shfl_xor(s4[3], 4);
;     const float e0 = (b1 ? d2 : d0) + __shfl_xor(b1 ? d0 : d2, 2), e1 = (b1 ? d3 : d1) + __shfl_xor(b1 ? d1 : d3, 2);
;     float q1 = (b0 ? e1 : e0) + __shfl_xor(b0 ? e0 : e1, 1);
;     q1 += __shfl_xor(q1, 16); q1 += __shfl_xor(q1, 32);
;     return q1;
; __device__ __forceinline__ void norm_rows2(const f32x4 (&xa)[4], const f32x4 (&xb)[4], const LAS float* gsa, const LAS float* sha, const LAS float* gsb, const LAS float* shb, const LAS float* WgT, ...
;     ...
;     const float qa = bfly16(pa[0], pa[1], pa[2], pa[3], lane), qb = bfly16(pb[0], pb[1], pb[2], pb[3], lane);
;     if (lane < 16) { const float gbv = gate_b[lane]; const bool ls = (lane >> 2) & 1;
;         const float prea = qa + gbv, preb = qb + gbv;
;         ga[0] = ls ? log_sigmoid(prea) : prea; gb[0] = ls ? log_sigmoid(preb) : preb; }
	v_add_f32_e32 v28, v196, v197
	v_add_f32_e32 v29, v198, v199
	v_add_f32_e32 v82, v200, v201
	v_add_f32_e32 v83, v202, v203
	v_add_f32_e32 v84, v204, v205
	v_add_f32_e32 v85, v206, v207
	v_add_f32_e32 v90, v208, v209
	v_add_f32_e32 v91, v210, v211
	v_add_f32_e32 v92, v212, v213
	v_add_f32_e32 v93, v214, v215
	v_add_f32_e32 v12, v216, v217
	v_add_f32_e32 v13, v218, v219
	v_add_f32_e32 v10, v220, v221
	v_add_f32_e32 v11, v222, v223
	v_cndmask_b32_e64 v21, v85, v11, s[6:7]
	v_cndmask_b32_e64 v20, v84, v10, s[6:7]
	v_add_f32_dpp v110, v22, v22 row_mirror row_mask:0xf bank_mask:0x3
	v_add_f32_dpp v110, v86, v86 row_mirror row_mask:0xf bank_mask:0xc
	v_add_f32_dpp v114, v78, v78 row_mirror row_mask:0xf bank_mask:0x3
	v_add_f32_dpp v114, v2, v2 row_mirror row_mask:0xf bank_mask:0xc
	v_add_f32_dpp v118, v26, v26 row_mirror row_mask:0xf bank_mask:0x3
	v_add_f32_dpp v118, v90, v90 row_mirror row_mask:0xf bank_mask:0xc
	v_add_f32_dpp v122, v82, v82 row_mirror row_mask:0xf bank_mask:0x3
	v_add_f32_dpp v122, v12, v12 row_mirror row_mask:0xf bank_mask:0xc
	v_add_f32_dpp v111, v23, v23 row_mirror row_mask:0xf bank_mask:0x3
	v_add_f32_dpp v111, v87, v87 row_mirror row_mask:0xf bank_mask:0xc
	v_add_f32_dpp v115, v79, v79 row_mirror row_mask:0xf bank_mask:0x3
	v_add_f32_dpp v115, v3, v3 row_mirror row_mask:0xf bank_mask:0xc
	v_add_f32_dpp v119, v27, v27 row_mirror row_mask:0xf bank_mask:0x3
	v_add_f32_dpp v119, v91, v91 row_mirror row_mask:0xf bank_mask:0xc
	v_add_f32_dpp v123, v83, v83 row_mirror row_mask:0xf bank_mask:0x3
	v_add_f32_dpp v123, v13, v13 row_mirror row_mask:0xf bank_mask:0xc
	v_add_f32_dpp v112, v24, v24 row_mirror row_mask:0xf bank_mask:0x3
	v_add_f32_dpp v112, v88, v88 row_mirror row_mask:0xf bank_mask:0xc
	v_add_f32_dpp v116, v80, v80 row_mirror row_mask:0xf bank_mask:0x3
	v_add_f32_dpp v116, v0, v0 row_mirror row_mask:0xf bank_mask:0xc
	v_add_f32_dpp v120, v28, v28 row_mirror row_mask:0xf bank_mask:0x3
	v_add_f32_dpp v120, v92, v92 row_mirror row_mask:0xf bank_mask:0xc
	v_add_f32_dpp v124, v84, v84 row_mirror row_mask:0xf bank_mask:0x3
	v_add_f32_dpp v124, v10, v10 row_mirror row_mask:0xf bank_mask:0xc
	v_add_f32_dpp v113, v25, v25 row_mirror row_mask:0xf bank_mask:0x3
	v_add_f32_dpp v113, v89, v89 row_mirror row_mask:0xf bank_mask:0xc
	v_add_f32_dpp v117, v81, v81 row_mirror row_mask:0xf bank_mask:0x3
	v_add_f32_dpp v117, v1, v1 row_mirror row_mask:0xf bank_mask:0xc
	v_add_f32_dpp v121, v29, v29 row_mirror row_mask:0xf bank_mask:0x3
	v_add_f32_dpp v121, v93, v93 row_mirror row_mask:0xf bank_mask:0xc
	v_add_f32_dpp v125, v85, v85 row_mirror row_mask:0xf bank_mask:0x3
	v_add_f32_dpp v125, v11, v11 row_mirror row_mask:0xf bank_mask:0xc
	v_add_f32_dpp v126, v110, v110 row_half_mirror row_mask:0xf bank_mask:0x5
	v_add_f32_dpp v126, v114, v114 row_half_mirror row_mask:0xf bank_mask:0xa
	v_add_f32_dpp v130, v118, v118 row_half_mirror row_mask:0xf bank_mask:0x5
	v_add_f32_dpp v130, v122, v122 row_half_mirror row_mask:0xf bank_mask:0xa
	v_add_f32_dpp v127, v111, v111 row_half_mirror row_mask:0xf bank_mask:0x5
	v_add_f32_dpp v127, v115, v115 row_half_mirror row_mask:0xf bank_mask:0xa
	v_add_f32_dpp v131, v119, v119 row_half_mirror row_mask:0xf bank_mask:0x5
	v_add_f32_dpp v131, v123, v123 row_half_mirror row_mask:0xf bank_mask:0xa
	v_add_f32_dpp v128, v112, v112 row_half_mirror row_mask:0xf bank_mask:0x5
	v_add_f32_dpp v128, v116, v116 row_half_mirror row_mask:0xf bank_mask:0xa
	v_add_f32_dpp v132, v120, v120 row_half_mirror row_mask:0xf bank_mask:0x5
	v_add_f32_dpp v132, v124, v124 row_half_mirror row_mask:0xf bank_mask:0xa
	v_add_f32_dpp v129, v113, v113 row_half_mirror row_mask:0xf bank_mask:0x5
	v_add_f32_dpp v129, v117, v117 row_half_mirror row_mask:0xf bank_mask:0xa
	v_add_f32_dpp v133, v121, v121 row_half_mirror row_mask:0xf bank_mask:0x5
	v_add_f32_dpp v133, v125, v125 row_half_mirror row_mask:0xf bank_mask:0xa
	v_cndmask_b32_e64 v134, v128, v126, s[12:13]
	v_cndmask_b32_e64 v135, v126, v128, s[12:13]
	v_cndmask_b32_e64 v136, v129, v127, s[12:13]
	v_cndmask_b32_e64 v137, v127, v129, s[12:13]
	v_cndmask_b32_e64 v138, v132, v130, s[12:13]
	v_cndmask_b32_e64 v139, v130, v132, s[12:13]
	v_cndmask_b32_e64 v140, v133, v131, s[12:13]
	v_cndmask_b32_e64 v141, v131, v133, s[12:13]
	v_add_f32_dpp v134, v135, v134 quad_perm:[2,3,0,1] row_mask:0xf bank_mask:0xf
	v_add_f32_dpp v136, v137, v136 quad_perm:[2,3,0,1] row_mask:0xf bank_mask:0xf
	v_add_f32_dpp v138, v139, v138 quad_perm:[2,3,0,1] row_mask:0xf bank_mask:0xf
	v_add_f32_dpp v140, v141, v140 quad_perm:[2,3,0,1] row_mask:0xf bank_mask:0xf
	v_cndmask_b32_e64 v143, v134, v136, s[14:15]
	v_cndmask_b32_e64 v127, v138, v140, s[14:15]
	v_cndmask_b32_e64 v142, v136, v134, s[14:15]
	v_cndmask_b32_e64 v126, v140, v138, s[14:15]
	v_add_f32_dpp v1, v143, v142 quad_perm:[1,0,3,2] row_mask:0xf bank_mask:0xf
	v_add_f32_dpp v0, v127, v126 quad_perm:[1,0,3,2] row_mask:0xf bank_mask:0xf
	v_mov_b32_e32 v2, v0
	v_mov_b32_e32 v3, v1
	s_nop 1
	v_permlane16_swap_b32_e32 v2, v0
	v_permlane16_swap_b32_e32 v3, v1
	s_waitcnt lgkmcnt(0)
	v_pk_add_f32 v[0:1], v[0:1], v[2:3]
	v_mov_b32_e32 v2, v0
	v_mov_b32_e32 v3, v1
	s_nop 1
	v_permlane32_swap_b32_e32 v2, v0
	v_permlane32_swap_b32_e32 v3, v1
	s_and_saveexec_b64 s[30:31], s[16:17]
	s_cbranch_execz .LBB0_109
	s_waitcnt lgkmcnt(0)
	v_pk_add_f32 v[0:1], v[0:1], v[2:3]
	v_pk_add_f32 v[0:1], v[0:1], v[244:245] op_sel_hi:[1,0]
	s_and_saveexec_b64 s[80:81], s[10:11]
	s_cbranch_execz .LBB0_108
; __device__ __forceinline__ float log_sigmoid(float x) { return fminf(x, 0.f) - log1pf(expf(-fabsf(x))); }
; __device__ __forceinline__ void norm_rows2(const f32x4 (&xa)[4], const f32x4 (&xb)[4], const LAS float* gsa, const LAS float* sha, const LAS float* gsb, const LAS float* shb, const LAS float* WgT, ...
;     ...
;     if (lane < 16) { const float gbv = gate_b[lane]; const bool ls = (lane >> 2) & 1;
;         const float prea = qa + gbv, preb = qb + gbv;
;         ga[0] = ls ? log_sigmoid(prea) : prea; gb[0] = ls ? log_sigmoid(preb) : preb; }
	v_mul_f32_e64 v2, |v0|, s35
	v_rndne_f32_e32 v3, v2
	v_sub_f32_e32 v4, v2, v3
	v_fma_f32 v2, |v0|, s35, -v2
	v_fma_f32 v2, |v0|, s47, v2
	v_add_f32_e32 v2, v4, v2
	v_exp_f32_e32 v4, v2
	v_cvt_i32_f32_e32 v3, v3
	v_cmp_ngt_f32_e64 s[28:29], |v0|, s53
	v_max_f32_e32 v2, v0, v0
	v_min_f32_e32 v2, 0, v2
	v_ldexp_f32 v3, v4, v3
	v_cndmask_b32_e64 v3, 0, v3, s[28:29]
	v_cmp_nlt_f32_e64 s[28:29], |v0|, s75
	s_nop 1
	v_cndmask_b32_e64 v30, v107, v3, s[28:29]
	v_add_f32_e32 v6, 1.0, v30
	v_add_f32_e32 v0, -1.0, v6
	v_sub_f32_e32 v3, v0, v6
	v_add_f32_e32 v3, 1.0, v3
	v_sub_f32_e32 v0, v30, v0
	v_add_f32_e32 v7, v0, v3
	v_mul_f32_e64 v0, |v1|, s35
	v_rndne_f32_e32 v3, v0
	v_sub_f32_e32 v9, v0, v3
	v_fma_f32 v0, |v1|, s35, -v0
	v_fma_f32 v0, |v1|, s47, v0
	v_add_f32_e32 v0, v9, v0
	v_exp_f32_e32 v0, v0
	v_cvt_i32_f32_e32 v9, v3
	v_cmp_ngt_f32_e64 s[28:29], |v1|, s53
	v_cvt_f64_f32_e32 v[4:5], v6
	v_frexp_exp_i32_f64_e32 v4, v[4:5]
	v_ldexp_f32 v0, v0, v9
	v_cndmask_b32_e64 v0, 0, v0, s[28:29]
	v_cmp_nlt_f32_e64 s[28:29], |v1|, s75
	v_max_f32_e32 v3, v1, v1
	v_frexp_mant_f32_e32 v8, v6
	v_cndmask_b32_e64 v31, v107, v0, s[28:29]
	v_add_f32_e32 v5, 1.0, v31
	v_add_f32_e32 v0, -1.0, v5
	v_sub_f32_e32 v1, v0, v5
	v_add_f32_e32 v1, 1.0, v1
	v_sub_f32_e32 v0, v31, v0
	v_add_f32_e32 v9, v0, v1
	v_frexp_mant_f32_e32 v10, v5
	v_cvt_f64_f32_e32 v[0:1], v5
	v_frexp_exp_i32_f64_e32 v0, v[0:1]
	v_cmp_gt_f32_e64 s[28:29], s79, v10
	v_min_f32_e32 v3, 0, v3
	s_nop 0
	v_subbrev_co_u32_e64 v22, s[28:29], 0, v0, s[28:29]
	v_cmp_gt_f32_e64 s[28:29], s79, v8
	s_nop 1
	v_subbrev_co_u32_e64 v23, s[28:29], 0, v4, s[28:29]
	v_sub_u32_e32 v1, 0, v23
	v_ldexp_f32 v0, v6, v1
	v_sub_u32_e32 v6, 0, v22
	v_ldexp_f32 v4, v7, v1
	v_ldexp_f32 v1, v5, v6
	v_ldexp_f32 v5, v9, v6
	v_pk_add_f32 v[6:7], v[0:1], 1.0 op_sel_hi:[1,0]
	v_pk_add_f32 v[14:15], v[0:1], -1.0 op_sel_hi:[1,0]
	v_pk_add_f32 v[8:9], v[6:7], -1.0 op_sel_hi:[1,0]
	v_pk_add_f32 v[16:17], v[14:15], 1.0 op_sel_hi:[1,0]
	v_pk_add_f32 v[8:9], v[0:1], v[8:9] neg_lo:[0,1] neg_hi:[0,1]
	v_pk_add_f32 v[0:1], v[0:1], v[16:17] neg_lo:[0,1] neg_hi:[0,1]
	v_pk_add_f32 v[8:9], v[4:5], v[8:9]
	v_pk_add_f32 v[0:1], v[4:5], v[0:1]
	v_pk_add_f32 v[10:11], v[6:7], v[8:9]
	v_pk_add_f32 v[4:5], v[14:15], v[0:1]
	v_rcp_f32_e32 v12, v10
	v_rcp_f32_e32 v13, v11
	v_pk_add_f32 v[6:7], v[6:7], v[10:11] neg_lo:[0,1] neg_hi:[0,1]
	v_pk_add_f32 v[14:15], v[14:15], v[4:5] neg_lo:[0,1] neg_hi:[0,1]
	v_pk_add_f32 v[6:7], v[8:9], v[6:7]
	v_pk_mul_f32 v[8:9], v[4:5], v[12:13]
	v_pk_add_f32 v[0:1], v[0:1], v[14:15]
	v_pk_mul_f32 v[14:15], v[10:11], v[8:9]
	v_cmp_neq_f32_e64 s[28:29], s77, v30
	v_pk_fma_f32 v[16:17], v[8:9], v[10:11], v[14:15] neg_lo:[0,0,1] neg_hi:[0,0,1]
	s_nop 0
	v_pk_fma_f32 v[16:17], v[8:9], v[6:7], v[16:17]
	s_nop 0
	v_pk_add_f32 v[18:19], v[14:15], v[16:17]
	s_nop 0
	v_pk_add_f32 v[20:21], v[4:5], v[18:19] neg_lo:[0,1] neg_hi:[0,1]
	v_pk_add_f32 v[14:15], v[18:19], v[14:15] neg_lo:[0,1] neg_hi:[0,1]
	v_pk_add_f32 v[4:5], v[4:5], v[20:21] neg_lo:[0,1] neg_hi:[0,1]
	s_nop 0
	v_pk_add_f32 v[4:5], v[4:5], v[18:19] neg_lo:[0,1] neg_hi:[0,1]
	s_nop 0
	v_pk_add_f32 v[0:1], v[0:1], v[4:5]
	v_pk_add_f32 v[4:5], v[14:15], v[16:17] neg_lo:[0,1] neg_hi:[0,1]
	s_nop 0
	v_pk_add_f32 v[0:1], v[4:5], v[0:1]
	s_nop 0
	v_pk_add_f32 v[4:5], v[20:21], v[0:1]
	s_nop 0
	v_pk_mul_f32 v[14:15], v[12:13], v[4:5]
	s_nop 0
	v_pk_mul_f32 v[16:17], v[10:11], v[14:15]
	s_nop 0
	v_pk_fma_f32 v[10:11], v[14:15], v[10:11], v[16:17] neg_lo:[0,0,1] neg_hi:[0,0,1]
	s_nop 0
	v_pk_fma_f32 v[6:7], v[14:15], v[6:7], v[10:11]
	v_pk_add_f32 v[10:11], v[20:21], v[4:5] neg_lo:[0,1] neg_hi:[0,1]
	s_nop 0
	v_pk_add_f32 v[0:1], v[0:1], v[10:11]
	v_pk_add_f32 v[10:11], v[16:17], v[6:7]
	s_nop 0
	v_pk_add_f32 v[18:19], v[4:5], v[10:11] neg_lo:[0,1] neg_hi:[0,1]
	v_pk_add_f32 v[16:17], v[10:11], v[16:17] neg_lo:[0,1] neg_hi:[0,1]
	v_pk_add_f32 v[4:5], v[4:5], v[18:19] neg_lo:[0,1] neg_hi:[0,1]
	s_nop 0
	v_pk_add_f32 v[4:5], v[4:5], v[10:11] neg_lo:[0,1] neg_hi:[0,1]
	s_nop 0
	v_pk_add_f32 v[0:1], v[0:1], v[4:5]
	v_pk_add_f32 v[4:5], v[16:17], v[6:7] neg_lo:[0,1] neg_hi:[0,1]
	s_nop 0
	v_pk_add_f32 v[0:1], v[4:5], v[0:1]
	v_pk_add_f32 v[4:5], v[8:9], v[14:15]
	v_pk_add_f32 v[0:1], v[18:19], v[0:1]
	v_pk_add_f32 v[6:7], v[4:5], v[8:9] neg_lo:[0,1] neg_hi:[0,1]
	v_pk_mul_f32 v[0:1], v[12:13], v[0:1]
	v_pk_add_f32 v[6:7], v[14:15], v[6:7] neg_lo:[0,1] neg_hi:[0,1]
; __device__ __forceinline__ float log_sigmoid(float x) { return fminf(x, 0.f) - log1pf(expf(-fabsf(x))); }
; __device__ __forceinline__ void norm_rows2(const f32x4 (&xa)[4], const f32x4 (&xb)[4], const LAS float* gsa, const LAS float* sha, const LAS float* gsb, const LAS float* shb, const LAS float* WgT, ...
;     ...
;     if (lane < 16) { const float gbv = gate_b[lane]; const bool ls = (lane >> 2) & 1;
;         const float prea = qa + gbv, preb = qb + gbv;
;         ga[0] = ls ? log_sigmoid(prea) : prea; gb[0] = ls ? log_sigmoid(preb) : preb; }
	v_cvt_f32_i32_e32 v9, v22
	v_pk_add_f32 v[0:1], v[6:7], v[0:1]
	v_cvt_f32_i32_e32 v8, v23
	v_pk_add_f32 v[6:7], v[4:5], v[0:1]
	v_pk_mul_f32 v[14:15], v[8:9], s[76:77] op_sel_hi:[1,0]
	v_pk_mul_f32 v[10:11], v[6:7], v[6:7]
	v_pk_add_f32 v[4:5], v[6:7], v[4:5] neg_lo:[0,1] neg_hi:[0,1]
	v_pk_fma_f32 v[12:13], v[10:11], s[52:53], v[52:53] op_sel_hi:[1,0,0]
	v_pk_add_f32 v[0:1], v[0:1], v[4:5] neg_lo:[0,1] neg_hi:[0,1]
	v_ldexp_f32 v4, v6, 1
	v_pk_fma_f32 v[12:13], v[10:11], v[12:13], s[74:75] op_sel_hi:[1,1,0]
	v_ldexp_f32 v5, v7, 1
	v_pk_mul_f32 v[6:7], v[6:7], v[10:11]
	v_pk_fma_f32 v[16:17], v[8:9], s[76:77], v[14:15] op_sel_hi:[1,0,1] neg_lo:[0,0,1] neg_hi:[0,0,1]
	v_pk_mul_f32 v[6:7], v[6:7], v[12:13]
	v_mov_b32_e32 v19, v5
	v_pk_add_f32 v[10:11], v[4:5], v[6:7]
	v_ldexp_f32 v0, v0, 1
	v_pk_add_f32 v[4:5], v[10:11], v[4:5] neg_lo:[0,1] neg_hi:[0,1]
	v_pk_fma_f32 v[8:9], v[8:9], s[78:79], v[16:17] op_sel_hi:[1,0,1]
	v_ldexp_f32 v1, v1, 1
	v_pk_add_f32 v[4:5], v[6:7], v[4:5] neg_lo:[0,1] neg_hi:[0,1]
	v_mov_b32_e32 v12, v14
	v_mov_b32_e32 v13, v7
	v_mov_b32_e32 v18, v8
	v_pk_add_f32 v[6:7], v[0:1], v[4:5]
	v_mov_b32_e32 v4, v14
	v_mov_b32_e32 v0, v8
	v_pk_add_f32 v[12:13], v[12:13], v[18:19]
	v_pk_add_f32 v[18:19], v[4:5], v[0:1]
	v_mov_b32_e32 v0, v10
	v_mov_b32_e32 v4, v6
	v_pk_add_f32 v[16:17], v[14:15], v[8:9]
	v_pk_add_f32 v[0:1], v[0:1], v[4:5]
	v_pk_add_f32 v[4:5], v[10:11], v[6:7]
	v_mov_b32_e32 v20, v16
	v_mov_b32_e32 v21, v15
	v_mov_b32_e32 v22, v4
	v_mov_b32_e32 v23, v9
	v_pk_add_f32 v[0:1], v[12:13], v[0:1]
	v_pk_add_f32 v[12:13], v[16:17], v[4:5]
	v_pk_add_f32 v[24:25], v[20:21], v[22:23]
	v_mov_b32_e32 v26, v4
	v_mov_b32_e32 v27, v13
	v_mov_b32_e32 v28, v10
	v_mov_b32_e32 v29, v17
	v_pk_add_f32 v[20:21], v[24:25], v[20:21] neg_lo:[0,1] neg_hi:[0,1]
	v_pk_add_f32 v[26:27], v[26:27], v[28:29] neg_lo:[0,1] neg_hi:[0,1]
	v_pk_add_f32 v[24:25], v[16:17], v[14:15] neg_lo:[0,1] neg_hi:[0,1]
	v_pk_add_f32 v[22:23], v[22:23], v[20:21] neg_lo:[0,1] neg_hi:[0,1]
	v_mov_b32_e32 v28, v16
	v_mov_b32_e32 v29, v13
	v_mov_b32_e32 v15, v27
	v_mov_b32_e32 v21, v11
	v_pk_add_f32 v[10:11], v[4:5], v[10:11] neg_lo:[0,1] neg_hi:[0,1]
	v_pk_add_f32 v[14:15], v[28:29], v[14:15] neg_lo:[0,1] neg_hi:[0,1]
	v_pk_add_f32 v[24:25], v[8:9], v[24:25] neg_lo:[0,1] neg_hi:[0,1]
	v_pk_add_f32 v[0:1], v[0:1], v[20:21] neg_lo:[0,1] neg_hi:[0,1]
	v_pk_add_f32 v[10:11], v[6:7], v[10:11] neg_lo:[0,1] neg_hi:[0,1]
	v_mov_b32_e32 v9, v17
	v_mov_b32_e32 v7, v5
	v_pk_add_f32 v[0:1], v[18:19], v[0:1] neg_lo:[0,1] neg_hi:[0,1]
	v_pk_add_f32 v[8:9], v[8:9], v[14:15] neg_lo:[0,1] neg_hi:[0,1]
	v_pk_add_f32 v[4:5], v[6:7], v[26:27] neg_lo:[0,1] neg_hi:[0,1]
	v_pk_add_f32 v[14:15], v[22:23], v[0:1]
	v_pk_add_f32 v[6:7], v[4:5], v[8:9]
	v_mov_b32_e32 v5, v1
	v_pk_add_f32 v[0:1], v[24:25], v[4:5]
	v_mov_b32_e32 v9, v23
	v_pk_add_f32 v[0:1], v[0:1], v[8:9] neg_lo:[0,1] neg_hi:[0,1]
	v_mov_b32_e32 v4, v6
	v_mov_b32_e32 v5, v15
	v_pk_add_f32 v[4:5], v[4:5], v[0:1] neg_lo:[0,1] neg_hi:[0,1]
	v_pk_add_f32 v[0:1], v[10:11], v[0:1] neg_lo:[0,1] neg_hi:[0,1]
	v_pk_add_f32 v[4:5], v[8:9], v[4:5] neg_lo:[0,1] neg_hi:[0,1]
	s_nop 0
	v_pk_add_f32 v[0:1], v[0:1], v[4:5]
	v_pk_add_f32 v[4:5], v[14:15], v[6:7]
	s_nop 0
	v_pk_add_f32 v[6:7], v[12:13], v[4:5]
	s_nop 0
	v_pk_add_f32 v[8:9], v[6:7], v[12:13] neg_lo:[0,1] neg_hi:[0,1]
	s_nop 0
	v_pk_add_f32 v[4:5], v[4:5], v[8:9] neg_lo:[0,1] neg_hi:[0,1]
	s_nop 0
	v_pk_add_f32 v[0:1], v[0:1], v[4:5]
	s_nop 0
	v_pk_add_f32 v[0:1], v[6:7], v[0:1]
	s_nop 0
	v_cndmask_b32_e64 v0, v107, v0, s[28:29]
	v_cmp_neq_f32_e64 s[28:29], s77, v31
	s_nop 1
	v_cndmask_b32_e64 v1, v107, v1, s[28:29]
	v_cmp_lt_f32_e64 s[28:29], |v31|, s92
	s_nop 1
	v_cndmask_b32_e64 v1, v1, v31, s[28:29]
	v_cmp_lt_f32_e64 s[28:29], |v30|, s92
	s_nop 1
	v_cndmask_b32_e64 v0, v0, v30, s[28:29]
	v_pk_add_f32 v[0:1], v[2:3], v[0:1] neg_lo:[0,1] neg_hi:[0,1]
	s_branch .LBB0_108
.LBB0_113:
	s_nop 0
	s_waitcnt vmcnt(0)
	s_barrier
	v_cmp_eq_u32_e32 vcc, 0, v224
	s_and_saveexec_b64 s[4:5], vcc
	s_cbranch_execz .Lpa1_skip
	v_readlane_b32 s6, v254, 5
	s_lshl_b32 s7, s6, 2
	s_lshl_b32 s7, 1, s7
	s_cmp_lt_u32 s6, 8
	s_cselect_b32 s7, s7, 0
	s_and_b32 s8, s2, 7
	s_lshl_b32 s8, s8, 3
	s_lshr_b32 s9, s2, 5
	s_add_u32 s8, s8, s9
	s_lshl_b32 s8, s8, 8
	s_add_u32 s8, s8, 0xff84040
	s_add_u32 s8, s70, s8
	s_addc_u32 s9, s71, 0
	v_mov_b32_e32 v0, 0
	v_mov_b32_e32 v1, s7
	global_atomic_add v0, v1, s[8:9]
